# row passes (st2/7/10): counted vmcnt waits per row instead of one vmcnt(0) behind all 64 row loads
# speedup vs baseline: 1.0077x; 1.0077x over previous
.LBB0_562:
	s_lshl_b32 s6, s24, 3
	s_ashr_i32 s7, s6, 31
	v_lshlrev_b32_e32 v49, 2, v116
	s_lshl_b64 s[10:11], s[6:7], 10
	v_mov_b32_e32 v217, s11
	v_or_b32_e32 v216, s10, v49
	v_lshlrev_b64 v[66:67], 1, v[216:217]
	v_lshl_add_u64 v[218:219], s[8:9], 0, v[66:67]
	v_lshl_add_u64 v[66:67], s[38:39], 0, v[66:67]
	global_load_dwordx2 v[90:91], v[218:219], off
	global_load_dwordx2 v[224:225], v[218:219], off offset:512
	global_load_dwordx2 v[222:223], v[218:219], off offset:1024
	global_load_dwordx2 v[220:221], v[218:219], off offset:1536
	global_load_dwordx2 v[86:87], v[66:67], off
	global_load_dwordx2 v[88:89], v[66:67], off offset:512
	global_load_dwordx2 v[92:93], v[66:67], off offset:1024
	global_load_dwordx2 v[230:231], v[66:67], off offset:1536
	s_or_b32 s10, s6, 1
	s_ashr_i32 s11, s10, 31
	s_lshl_b64 s[10:11], s[10:11], 10
	v_or_b32_e32 v196, s10, v49
	s_or_b32 s10, s6, 2
	v_mov_b32_e32 v197, s11
	s_ashr_i32 s11, s10, 31
	s_lshl_b64 s[10:11], s[10:11], 10
	v_or_b32_e32 v176, s10, v49
	s_or_b32 s10, s6, 3
	v_mov_b32_e32 v177, s11
	s_ashr_i32 s11, s10, 31
	s_lshl_b64 s[10:11], s[10:11], 10
	v_lshlrev_b64 v[66:67], 1, v[196:197]
	v_or_b32_e32 v156, s10, v49
	s_or_b32 s10, s6, 4
	v_lshl_add_u64 v[198:199], s[8:9], 0, v[66:67]
	v_lshl_add_u64 v[66:67], s[38:39], 0, v[66:67]
	v_mov_b32_e32 v157, s11
	s_ashr_i32 s11, s10, 31
	global_load_dwordx2 v[206:207], v[198:199], off
	global_load_dwordx2 v[204:205], v[198:199], off offset:512
	global_load_dwordx2 v[202:203], v[198:199], off offset:1024
	global_load_dwordx2 v[200:201], v[198:199], off offset:1536
	global_load_dwordx2 v[214:215], v[66:67], off
	global_load_dwordx2 v[212:213], v[66:67], off offset:512
	global_load_dwordx2 v[210:211], v[66:67], off offset:1024
	global_load_dwordx2 v[208:209], v[66:67], off offset:1536
	v_lshlrev_b64 v[66:67], 1, v[176:177]
	s_lshl_b64 s[10:11], s[10:11], 10
	v_lshl_add_u64 v[178:179], s[8:9], 0, v[66:67]
	v_lshl_add_u64 v[66:67], s[38:39], 0, v[66:67]
	v_or_b32_e32 v134, s10, v49
	s_or_b32 s10, s6, 5
	global_load_dwordx2 v[186:187], v[178:179], off
	global_load_dwordx2 v[184:185], v[178:179], off offset:512
	global_load_dwordx2 v[182:183], v[178:179], off offset:1024
	global_load_dwordx2 v[180:181], v[178:179], off offset:1536
	global_load_dwordx2 v[194:195], v[66:67], off
	global_load_dwordx2 v[192:193], v[66:67], off offset:512
	global_load_dwordx2 v[190:191], v[66:67], off offset:1024
	global_load_dwordx2 v[188:189], v[66:67], off offset:1536
	v_lshlrev_b64 v[66:67], 1, v[156:157]
	v_mov_b32_e32 v135, s11
	s_ashr_i32 s11, s10, 31
	v_lshl_add_u64 v[158:159], s[8:9], 0, v[66:67]
	v_lshl_add_u64 v[66:67], s[38:39], 0, v[66:67]
	s_lshl_b64 s[10:11], s[10:11], 10
	global_load_dwordx2 v[166:167], v[158:159], off
	global_load_dwordx2 v[164:165], v[158:159], off offset:512
	global_load_dwordx2 v[162:163], v[158:159], off offset:1024
	global_load_dwordx2 v[160:161], v[158:159], off offset:1536
	global_load_dwordx2 v[174:175], v[66:67], off
	global_load_dwordx2 v[172:173], v[66:67], off offset:512
	global_load_dwordx2 v[170:171], v[66:67], off offset:1024
	global_load_dwordx2 v[168:169], v[66:67], off offset:1536
	v_lshlrev_b64 v[66:67], 1, v[134:135]
	v_or_b32_e32 v114, s10, v49
	s_or_b32 s10, s6, 6
	v_lshl_add_u64 v[136:137], s[8:9], 0, v[66:67]
	v_lshl_add_u64 v[66:67], s[38:39], 0, v[66:67]
	v_mov_b32_e32 v115, s11
	s_ashr_i32 s11, s10, 31
	global_load_dwordx2 v[146:147], v[136:137], off
	global_load_dwordx2 v[142:143], v[136:137], off offset:512
	global_load_dwordx2 v[140:141], v[136:137], off offset:1024
	global_load_dwordx2 v[138:139], v[136:137], off offset:1536
	global_load_dwordx2 v[154:155], v[66:67], off
	global_load_dwordx2 v[152:153], v[66:67], off offset:512
	global_load_dwordx2 v[150:151], v[66:67], off offset:1024
	global_load_dwordx2 v[148:149], v[66:67], off offset:1536
	v_lshlrev_b64 v[66:67], 1, v[114:115]
	s_lshl_b64 s[10:11], s[10:11], 10
	v_lshl_add_u64 v[116:117], s[8:9], 0, v[66:67]
	v_lshl_add_u64 v[66:67], s[38:39], 0, v[66:67]
	v_mov_b32_e32 v95, s11
	v_or_b32_e32 v94, s10, v49
	s_or_b32 s6, s6, 7
	global_load_dwordx2 v[124:125], v[116:117], off
	global_load_dwordx2 v[122:123], v[116:117], off offset:512
	global_load_dwordx2 v[120:121], v[116:117], off offset:1024
	global_load_dwordx2 v[118:119], v[116:117], off offset:1536
	global_load_dwordx2 v[132:133], v[66:67], off
	global_load_dwordx2 v[130:131], v[66:67], off offset:512
	global_load_dwordx2 v[128:129], v[66:67], off offset:1024
	global_load_dwordx2 v[126:127], v[66:67], off offset:1536
	v_lshlrev_b64 v[66:67], 1, v[94:95]
	s_ashr_i32 s7, s6, 31
	v_lshl_add_u64 v[96:97], s[8:9], 0, v[66:67]
	v_lshl_add_u64 v[66:67], s[38:39], 0, v[66:67]
	s_lshl_b64 s[6:7], s[6:7], 10
	global_load_dwordx2 v[104:105], v[96:97], off
	global_load_dwordx2 v[102:103], v[96:97], off offset:512
	global_load_dwordx2 v[100:101], v[96:97], off offset:1024
	global_load_dwordx2 v[98:99], v[96:97], off offset:1536
	global_load_dwordx2 v[112:113], v[66:67], off
	global_load_dwordx2 v[110:111], v[66:67], off offset:512
	global_load_dwordx2 v[108:109], v[66:67], off offset:1024
	global_load_dwordx2 v[106:107], v[66:67], off offset:1536
	v_mov_b32_e32 v67, s7
	v_or_b32_e32 v66, s6, v49
	v_lshlrev_b64 v[70:71], 1, v[66:67]
	v_lshl_add_u64 v[68:69], s[8:9], 0, v[70:71]
	v_lshl_add_u64 v[78:79], s[38:39], 0, v[70:71]
	global_load_dwordx2 v[76:77], v[68:69], off
	global_load_dwordx2 v[74:75], v[68:69], off offset:512
	global_load_dwordx2 v[72:73], v[68:69], off offset:1024
	global_load_dwordx2 v[70:71], v[68:69], off offset:1536
	global_load_dwordx2 v[84:85], v[78:79], off
	global_load_dwordx2 v[82:83], v[78:79], off offset:512
	global_load_dwordx2 v[80:81], v[78:79], off offset:1024
	s_nop 0
	global_load_dwordx2 v[78:79], v[78:79], off offset:1536
	v_xor_b32_e32 v144, 4, v49
	v_xor_b32_e32 v251, 32, v49
	v_xor_b32_e32 v252, 64, v49
	s_waitcnt vmcnt(56)
	v_pk_add_f32 v[20:21], v[20:21], 1.0 op_sel_hi:[1,0]
	v_pk_add_f32 v[22:23], v[22:23], 1.0 op_sel_hi:[1,0]
	v_pk_mul_f32 v[20:21], v[48:49], v[20:21] op_sel_hi:[0,1]
	v_pk_mul_f32 v[22:23], v[48:49], v[22:23] op_sel_hi:[0,1]
	s_cmp_lg_u64 s[0:1], 0
	s_cselect_b64 s[8:9], -1, 0
	s_cmp_eq_u64 s[0:1], 0
	v_and_b32_e32 v237, 0xffff0000, v86
	v_and_b32_e32 v249, 0xffff0000, v87
	v_lshlrev_b32_e32 v236, 16, v86
	v_lshlrev_b32_e32 v248, 16, v87
	v_mul_f32_e32 v86, v249, v249
	v_and_b32_e32 v243, 0xffff0000, v89
	v_and_b32_e32 v242, 0xffff0000, v88
	v_lshlrev_b32_e32 v232, 16, v92
	v_and_b32_e32 v233, 0xffff0000, v92
	v_mul_f32_e32 v92, v237, v237
	v_pk_fma_f32 v[86:87], v[248:249], v[248:249], v[86:87] op_sel_hi:[1,1,0]
	v_lshlrev_b32_e32 v241, 16, v89
	v_lshlrev_b32_e32 v240, 16, v88
	v_pk_mul_f32 v[88:89], v[242:243], v[242:243]
	v_lshlrev_b32_e32 v234, 16, v93
	v_and_b32_e32 v235, 0xffff0000, v93
	v_lshlrev_b32_e32 v229, 16, v230
	v_pk_fma_f32 v[92:93], v[236:237], v[236:237], v[92:93] op_sel_hi:[1,1,0]
	v_pk_fma_f32 v[88:89], v[240:241], v[240:241], v[88:89]
	v_and_b32_e32 v227, 0xffff0000, v230
	v_mov_b32_e32 v228, v92
	v_mov_b32_e32 v238, v86
	v_mov_b32_e32 v239, v229
	v_mul_f32_e32 v226, v227, v227
	v_pk_add_f32 v[86:87], v[92:93], v[86:87]
	v_pk_mul_f32 v[92:93], v[228:229], v[238:239]
	v_pk_add_f32 v[88:89], v[88:89], v[88:89] op_sel:[0,1] op_sel_hi:[1,0]
	v_mov_b32_e32 v87, v93
	v_mov_b32_e32 v89, v226
	v_lshlrev_b32_e32 v230, 16, v231
	v_and_b32_e32 v231, 0xffff0000, v231
	v_pk_add_f32 v[86:87], v[86:87], v[88:89]
	v_mul_f32_e32 v88, v233, v233
	v_mul_f32_e32 v92, v235, v235
	v_mul_f32_e32 v246, v230, v230
	v_mul_f32_e32 v250, v231, v231
	v_pk_fma_f32 v[88:89], v[232:233], v[232:233], v[88:89] op_sel_hi:[1,1,0]
	v_pk_fma_f32 v[92:93], v[234:235], v[234:235], v[92:93] op_sel_hi:[1,1,0]
	v_mov_b32_e32 v89, v246
	v_mov_b32_e32 v93, v250
	v_pk_add_f32 v[88:89], v[88:89], v[92:93]
	v_xor_b32_e32 v228, 8, v49
	v_pk_add_f32 v[86:87], v[86:87], v[88:89]
	v_xor_b32_e32 v250, 16, v49
	v_add_f32_e32 v86, v86, v87
	ds_bpermute_b32 v87, v144, v86
	v_xor_b32_e32 v246, 0x80, v49
	v_pk_mul_f32 v[88:89], v[18:19], v[22:23]
	v_and_b32_e32 v19, 0xffff0000, v91
	s_waitcnt lgkmcnt(0)
	v_add_f32_e32 v86, v86, v87
	ds_bpermute_b32 v87, v228, v86
	s_waitcnt lgkmcnt(0)
	v_add_f32_e32 v86, v86, v87
	ds_bpermute_b32 v87, v250, v86
	s_waitcnt lgkmcnt(0)
	v_add_f32_e32 v86, v86, v87
	ds_bpermute_b32 v87, v251, v86
	s_waitcnt lgkmcnt(0)
	v_add_f32_e32 v92, v86, v87
	ds_bpermute_b32 v93, v252, v92
	v_pk_mul_f32 v[86:87], v[16:17], v[20:21]
	v_lshlrev_b32_e32 v16, 16, v90
	s_waitcnt lgkmcnt(0)
	v_add_f32_e32 v17, v92, v93
	ds_bpermute_b32 v18, v246, v17
	s_waitcnt lgkmcnt(0)
	v_add_f32_e32 v17, v17, v18
	v_fmamk_f32 v17, v17, 0x3a800000, v247
	v_mul_f32_e32 v18, 0x4b800000, v17
	v_cmp_gt_f32_e32 vcc, s35, v17
	s_nop 1
	v_cndmask_b32_e32 v17, v17, v18, vcc
	v_rsq_f32_e32 v20, v17
	v_and_b32_e32 v17, 0xffff0000, v90
	v_lshlrev_b32_e32 v18, 16, v91
	v_mul_f32_e32 v21, 0x45800000, v20
	v_cndmask_b32_e32 v238, v20, v21, vcc
	v_pk_mul_f32 v[20:21], v[238:239], v[236:237] op_sel_hi:[0,1]
	v_pk_mul_f32 v[22:23], v[238:239], v[248:249] op_sel_hi:[0,1]
	v_pk_fma_f32 v[18:19], v[88:89], v[22:23], v[18:19]
	v_pk_fma_f32 v[16:17], v[86:87], v[20:21], v[16:17]
	v_lshl_add_u64 v[236:237], v[216:217], 2, s[0:1]
	s_cbranch_scc1 .LBB0_573
	s_waitcnt vmcnt(0)
	global_store_dwordx4 v[236:237], v[16:19], off
	s_cbranch_execnz .LBB0_565

.LBB0_581:
	s_waitcnt vmcnt(56)
	v_and_b32_e32 v17, 0xffff0000, v214
	v_and_b32_e32 v19, 0xffff0000, v215
	v_lshlrev_b32_e32 v16, 16, v214
	v_lshlrev_b32_e32 v18, 16, v215
	v_mul_f32_e32 v20, v19, v19
	v_and_b32_e32 v23, 0xffff0000, v213
	v_and_b32_e32 v22, 0xffff0000, v212
	v_and_b32_e32 v29, 0xffff0000, v208
	v_mul_f32_e32 v28, v17, v17
	v_pk_fma_f32 v[42:43], v[18:19], v[18:19], v[20:21] op_sel_hi:[1,1,0]
	v_lshlrev_b32_e32 v21, 16, v213
	v_lshlrev_b32_e32 v20, 16, v212
	v_pk_mul_f32 v[24:25], v[22:23], v[22:23]
	v_lshlrev_b32_e32 v31, 16, v208
	v_pk_fma_f32 v[46:47], v[16:17], v[16:17], v[28:29] op_sel_hi:[1,1,0]
	v_pk_fma_f32 v[44:45], v[20:21], v[20:21], v[24:25]
	v_mov_b32_e32 v30, v46
	v_mov_b32_e32 v48, v42
	v_mov_b32_e32 v49, v31
	v_and_b32_e32 v25, 0xffff0000, v210
	v_mul_f32_e32 v208, v29, v29
	v_pk_add_f32 v[42:43], v[46:47], v[42:43]
	v_pk_mul_f32 v[46:47], v[30:31], v[48:49]
	v_pk_add_f32 v[44:45], v[44:45], v[44:45] op_sel:[0,1] op_sel_hi:[1,0]
	v_lshlrev_b32_e32 v24, 16, v210
	v_and_b32_e32 v27, 0xffff0000, v211
	v_mov_b32_e32 v43, v47
	v_mov_b32_e32 v45, v208
	v_mul_f32_e32 v28, v25, v25
	v_lshlrev_b32_e32 v26, 16, v211
	v_lshlrev_b32_e32 v40, 16, v209
	v_and_b32_e32 v41, 0xffff0000, v209
	v_pk_add_f32 v[42:43], v[42:43], v[44:45]
	v_pk_fma_f32 v[44:45], v[24:25], v[24:25], v[28:29] op_sel_hi:[1,1,0]
	v_mul_f32_e32 v28, v27, v27
	v_mul_f32_e32 v209, v40, v40
	v_mul_f32_e32 v210, v41, v41
	v_pk_fma_f32 v[46:47], v[26:27], v[26:27], v[28:29] op_sel_hi:[1,1,0]
	v_mov_b32_e32 v45, v209
	v_mov_b32_e32 v47, v210
	v_pk_add_f32 v[44:45], v[44:45], v[46:47]
	v_lshlrev_b32_e32 v46, 16, v207
	v_pk_add_f32 v[42:43], v[42:43], v[44:45]
	v_lshlrev_b32_e32 v44, 16, v206
	v_add_f32_e32 v28, v42, v43
	ds_bpermute_b32 v30, v144, v28
	v_and_b32_e32 v45, 0xffff0000, v206
	v_and_b32_e32 v47, 0xffff0000, v207
	s_waitcnt lgkmcnt(0)
	v_add_f32_e32 v28, v28, v30
	ds_bpermute_b32 v30, v228, v28
	s_waitcnt lgkmcnt(0)
	v_add_f32_e32 v28, v28, v30
	ds_bpermute_b32 v30, v250, v28
	s_waitcnt lgkmcnt(0)
	v_add_f32_e32 v28, v28, v30
	ds_bpermute_b32 v30, v251, v28
	s_waitcnt lgkmcnt(0)
	v_add_f32_e32 v28, v28, v30
	ds_bpermute_b32 v30, v252, v28
	s_waitcnt lgkmcnt(0)
	v_add_f32_e32 v28, v28, v30
	ds_bpermute_b32 v30, v246, v28
	s_waitcnt lgkmcnt(0)
	v_add_f32_e32 v28, v28, v30
	v_fmamk_f32 v28, v28, 0x3a800000, v247
	v_mul_f32_e32 v30, 0x4b800000, v28
	v_cmp_gt_f32_e32 vcc, s35, v28
	s_nop 1
	v_cndmask_b32_e32 v28, v28, v30, vcc
	v_rsq_f32_e32 v28, v28
	s_nop 0
	v_mul_f32_e32 v30, 0x45800000, v28
	v_cndmask_b32_e32 v42, v28, v30, vcc
	v_pk_mul_f32 v[16:17], v[42:43], v[16:17] op_sel_hi:[0,1]
	v_pk_mul_f32 v[18:19], v[42:43], v[18:19] op_sel_hi:[0,1]
	v_pk_fma_f32 v[18:19], v[88:89], v[18:19], v[46:47]
	v_pk_fma_f32 v[16:17], v[86:87], v[16:17], v[44:45]
	s_and_b64 vcc, exec, s[6:7]
	v_lshl_add_u64 v[44:45], v[196:197], 2, s[0:1]
	s_cbranch_vccnz .LBB0_835
	global_store_dwordx4 v[44:45], v[16:19], off
	s_cbranch_execnz .LBB0_584

.LBB0_595:
	s_waitcnt vmcnt(56)
	v_and_b32_e32 v17, 0xffff0000, v194
	v_and_b32_e32 v19, 0xffff0000, v195
	v_lshlrev_b32_e32 v16, 16, v194
	v_lshlrev_b32_e32 v18, 16, v195
	v_mul_f32_e32 v20, v19, v19
	v_and_b32_e32 v23, 0xffff0000, v193
	v_and_b32_e32 v22, 0xffff0000, v192
	v_and_b32_e32 v29, 0xffff0000, v188
	v_mul_f32_e32 v28, v17, v17
	v_pk_fma_f32 v[42:43], v[18:19], v[18:19], v[20:21] op_sel_hi:[1,1,0]
	v_lshlrev_b32_e32 v21, 16, v193
	v_lshlrev_b32_e32 v20, 16, v192
	v_pk_mul_f32 v[24:25], v[22:23], v[22:23]
	v_lshlrev_b32_e32 v31, 16, v188
	v_pk_fma_f32 v[46:47], v[16:17], v[16:17], v[28:29] op_sel_hi:[1,1,0]
	v_pk_fma_f32 v[44:45], v[20:21], v[20:21], v[24:25]
	v_mov_b32_e32 v30, v46
	v_mov_b32_e32 v48, v42
	v_mov_b32_e32 v49, v31
	v_and_b32_e32 v25, 0xffff0000, v190
	v_mul_f32_e32 v188, v29, v29
	v_pk_add_f32 v[42:43], v[46:47], v[42:43]
	v_pk_mul_f32 v[46:47], v[30:31], v[48:49]
	v_pk_add_f32 v[44:45], v[44:45], v[44:45] op_sel:[0,1] op_sel_hi:[1,0]
	v_lshlrev_b32_e32 v24, 16, v190
	v_and_b32_e32 v27, 0xffff0000, v191
	v_mov_b32_e32 v43, v47
	v_mov_b32_e32 v45, v188
	v_mul_f32_e32 v28, v25, v25
	v_lshlrev_b32_e32 v26, 16, v191
	v_lshlrev_b32_e32 v40, 16, v189
	v_and_b32_e32 v41, 0xffff0000, v189
	v_pk_add_f32 v[42:43], v[42:43], v[44:45]
	v_pk_fma_f32 v[44:45], v[24:25], v[24:25], v[28:29] op_sel_hi:[1,1,0]
	v_mul_f32_e32 v28, v27, v27
	v_mul_f32_e32 v189, v40, v40
	v_mul_f32_e32 v190, v41, v41
	v_pk_fma_f32 v[46:47], v[26:27], v[26:27], v[28:29] op_sel_hi:[1,1,0]
	v_mov_b32_e32 v45, v189
	v_mov_b32_e32 v47, v190
	v_pk_add_f32 v[44:45], v[44:45], v[46:47]
	v_lshlrev_b32_e32 v46, 16, v187
	v_pk_add_f32 v[42:43], v[42:43], v[44:45]
	v_lshlrev_b32_e32 v44, 16, v186
	v_add_f32_e32 v28, v42, v43
	ds_bpermute_b32 v30, v144, v28
	v_and_b32_e32 v45, 0xffff0000, v186
	v_and_b32_e32 v47, 0xffff0000, v187
	s_waitcnt lgkmcnt(0)
	v_add_f32_e32 v28, v28, v30
	ds_bpermute_b32 v30, v228, v28
	s_waitcnt lgkmcnt(0)
	v_add_f32_e32 v28, v28, v30
	ds_bpermute_b32 v30, v250, v28
	s_waitcnt lgkmcnt(0)
	v_add_f32_e32 v28, v28, v30
	ds_bpermute_b32 v30, v251, v28
	s_waitcnt lgkmcnt(0)
	v_add_f32_e32 v28, v28, v30
	ds_bpermute_b32 v30, v252, v28
	s_waitcnt lgkmcnt(0)
	v_add_f32_e32 v28, v28, v30
	ds_bpermute_b32 v30, v246, v28
	s_waitcnt lgkmcnt(0)
	v_add_f32_e32 v28, v28, v30
	v_fmamk_f32 v28, v28, 0x3a800000, v247
	v_mul_f32_e32 v30, 0x4b800000, v28
	v_cmp_gt_f32_e32 vcc, s35, v28
	s_nop 1
	v_cndmask_b32_e32 v28, v28, v30, vcc
	v_rsq_f32_e32 v28, v28
	s_nop 0
	v_mul_f32_e32 v30, 0x45800000, v28
	v_cndmask_b32_e32 v42, v28, v30, vcc
	v_pk_mul_f32 v[16:17], v[42:43], v[16:17] op_sel_hi:[0,1]
	v_pk_mul_f32 v[18:19], v[42:43], v[18:19] op_sel_hi:[0,1]
	v_pk_fma_f32 v[18:19], v[88:89], v[18:19], v[46:47]
	v_pk_fma_f32 v[16:17], v[86:87], v[16:17], v[44:45]
	s_and_b64 vcc, exec, s[6:7]
	v_lshl_add_u64 v[44:45], v[176:177], 2, s[0:1]
	s_cbranch_vccnz .LBB0_839
	global_store_dwordx4 v[44:45], v[16:19], off
	s_cbranch_execnz .LBB0_598

.LBB0_609:
	s_waitcnt vmcnt(56)
	v_and_b32_e32 v17, 0xffff0000, v174
	v_and_b32_e32 v19, 0xffff0000, v175
	v_lshlrev_b32_e32 v16, 16, v174
	v_lshlrev_b32_e32 v18, 16, v175
	v_mul_f32_e32 v20, v19, v19
	v_and_b32_e32 v23, 0xffff0000, v173
	v_and_b32_e32 v22, 0xffff0000, v172
	v_and_b32_e32 v29, 0xffff0000, v168
	v_mul_f32_e32 v28, v17, v17
	v_pk_fma_f32 v[42:43], v[18:19], v[18:19], v[20:21] op_sel_hi:[1,1,0]
	v_lshlrev_b32_e32 v21, 16, v173
	v_lshlrev_b32_e32 v20, 16, v172
	v_pk_mul_f32 v[24:25], v[22:23], v[22:23]
	v_lshlrev_b32_e32 v31, 16, v168
	v_pk_fma_f32 v[46:47], v[16:17], v[16:17], v[28:29] op_sel_hi:[1,1,0]
	v_pk_fma_f32 v[44:45], v[20:21], v[20:21], v[24:25]
	v_mov_b32_e32 v30, v46
	v_mov_b32_e32 v48, v42
	v_mov_b32_e32 v49, v31
	v_and_b32_e32 v25, 0xffff0000, v170
	v_mul_f32_e32 v168, v29, v29
	v_pk_add_f32 v[42:43], v[46:47], v[42:43]
	v_pk_mul_f32 v[46:47], v[30:31], v[48:49]
	v_pk_add_f32 v[44:45], v[44:45], v[44:45] op_sel:[0,1] op_sel_hi:[1,0]
	v_lshlrev_b32_e32 v24, 16, v170
	v_and_b32_e32 v27, 0xffff0000, v171
	v_mov_b32_e32 v43, v47
	v_mov_b32_e32 v45, v168
	v_mul_f32_e32 v28, v25, v25
	v_lshlrev_b32_e32 v26, 16, v171
	v_lshlrev_b32_e32 v40, 16, v169
	v_and_b32_e32 v41, 0xffff0000, v169
	v_pk_add_f32 v[42:43], v[42:43], v[44:45]
	v_pk_fma_f32 v[44:45], v[24:25], v[24:25], v[28:29] op_sel_hi:[1,1,0]
	v_mul_f32_e32 v28, v27, v27
	v_mul_f32_e32 v169, v40, v40
	v_mul_f32_e32 v170, v41, v41
	v_pk_fma_f32 v[46:47], v[26:27], v[26:27], v[28:29] op_sel_hi:[1,1,0]
	v_mov_b32_e32 v45, v169
	v_mov_b32_e32 v47, v170
	v_pk_add_f32 v[44:45], v[44:45], v[46:47]
	v_lshlrev_b32_e32 v46, 16, v167
	v_pk_add_f32 v[42:43], v[42:43], v[44:45]
	v_lshlrev_b32_e32 v44, 16, v166
	v_add_f32_e32 v28, v42, v43
	ds_bpermute_b32 v30, v144, v28
	v_and_b32_e32 v45, 0xffff0000, v166
	v_and_b32_e32 v47, 0xffff0000, v167
	s_waitcnt lgkmcnt(0)
	v_add_f32_e32 v28, v28, v30
	ds_bpermute_b32 v30, v228, v28
	s_waitcnt lgkmcnt(0)
	v_add_f32_e32 v28, v28, v30
	ds_bpermute_b32 v30, v250, v28
	s_waitcnt lgkmcnt(0)
	v_add_f32_e32 v28, v28, v30
	ds_bpermute_b32 v30, v251, v28
	s_waitcnt lgkmcnt(0)
	v_add_f32_e32 v28, v28, v30
	ds_bpermute_b32 v30, v252, v28
	s_waitcnt lgkmcnt(0)
	v_add_f32_e32 v28, v28, v30
	ds_bpermute_b32 v30, v246, v28
	s_waitcnt lgkmcnt(0)
	v_add_f32_e32 v28, v28, v30
	v_fmamk_f32 v28, v28, 0x3a800000, v247
	v_mul_f32_e32 v30, 0x4b800000, v28
	v_cmp_gt_f32_e32 vcc, s35, v28
	s_nop 1
	v_cndmask_b32_e32 v28, v28, v30, vcc
	v_rsq_f32_e32 v28, v28
	s_nop 0
	v_mul_f32_e32 v30, 0x45800000, v28
	v_cndmask_b32_e32 v42, v28, v30, vcc
	v_pk_mul_f32 v[16:17], v[42:43], v[16:17] op_sel_hi:[0,1]
	v_pk_mul_f32 v[18:19], v[42:43], v[18:19] op_sel_hi:[0,1]
	v_pk_fma_f32 v[18:19], v[88:89], v[18:19], v[46:47]
	v_pk_fma_f32 v[16:17], v[86:87], v[16:17], v[44:45]
	s_and_b64 vcc, exec, s[6:7]
	v_lshl_add_u64 v[44:45], v[156:157], 2, s[0:1]
	s_cbranch_vccnz .LBB0_843
	global_store_dwordx4 v[44:45], v[16:19], off
	s_cbranch_execnz .LBB0_612

.LBB0_623:
	s_waitcnt vmcnt(56)
	v_and_b32_e32 v17, 0xffff0000, v154
	v_and_b32_e32 v19, 0xffff0000, v155
	v_lshlrev_b32_e32 v16, 16, v154
	v_lshlrev_b32_e32 v18, 16, v155
	v_mul_f32_e32 v20, v19, v19
	v_and_b32_e32 v23, 0xffff0000, v153
	v_and_b32_e32 v22, 0xffff0000, v152
	v_and_b32_e32 v29, 0xffff0000, v148
	v_mul_f32_e32 v28, v17, v17
	v_pk_fma_f32 v[42:43], v[18:19], v[18:19], v[20:21] op_sel_hi:[1,1,0]
	v_lshlrev_b32_e32 v21, 16, v153
	v_lshlrev_b32_e32 v20, 16, v152
	v_pk_mul_f32 v[24:25], v[22:23], v[22:23]
	v_lshlrev_b32_e32 v31, 16, v148
	v_pk_fma_f32 v[46:47], v[16:17], v[16:17], v[28:29] op_sel_hi:[1,1,0]
	v_pk_fma_f32 v[44:45], v[20:21], v[20:21], v[24:25]
	v_mov_b32_e32 v30, v46
	v_mov_b32_e32 v48, v42
	v_mov_b32_e32 v49, v31
	v_and_b32_e32 v25, 0xffff0000, v150
	v_mul_f32_e32 v148, v29, v29
	v_pk_add_f32 v[42:43], v[46:47], v[42:43]
	v_pk_mul_f32 v[46:47], v[30:31], v[48:49]
	v_pk_add_f32 v[44:45], v[44:45], v[44:45] op_sel:[0,1] op_sel_hi:[1,0]
	v_lshlrev_b32_e32 v24, 16, v150
	v_and_b32_e32 v27, 0xffff0000, v151
	v_mov_b32_e32 v43, v47
	v_mov_b32_e32 v45, v148
	v_mul_f32_e32 v28, v25, v25
	v_lshlrev_b32_e32 v26, 16, v151
	v_lshlrev_b32_e32 v40, 16, v149
	v_and_b32_e32 v41, 0xffff0000, v149
	v_pk_add_f32 v[42:43], v[42:43], v[44:45]
	v_pk_fma_f32 v[44:45], v[24:25], v[24:25], v[28:29] op_sel_hi:[1,1,0]
	v_mul_f32_e32 v28, v27, v27
	v_mul_f32_e32 v149, v40, v40
	v_mul_f32_e32 v150, v41, v41
	v_pk_fma_f32 v[46:47], v[26:27], v[26:27], v[28:29] op_sel_hi:[1,1,0]
	v_mov_b32_e32 v45, v149
	v_mov_b32_e32 v47, v150
	v_pk_add_f32 v[44:45], v[44:45], v[46:47]
	v_lshlrev_b32_e32 v46, 16, v147
	v_pk_add_f32 v[42:43], v[42:43], v[44:45]
	v_lshlrev_b32_e32 v44, 16, v146
	v_add_f32_e32 v28, v42, v43
	ds_bpermute_b32 v30, v144, v28
	v_and_b32_e32 v45, 0xffff0000, v146
	v_and_b32_e32 v47, 0xffff0000, v147
	s_waitcnt lgkmcnt(0)
	v_add_f32_e32 v28, v28, v30
	ds_bpermute_b32 v30, v228, v28
	s_waitcnt lgkmcnt(0)
	v_add_f32_e32 v28, v28, v30
	ds_bpermute_b32 v30, v250, v28
	s_waitcnt lgkmcnt(0)
	v_add_f32_e32 v28, v28, v30
	ds_bpermute_b32 v30, v251, v28
	s_waitcnt lgkmcnt(0)
	v_add_f32_e32 v28, v28, v30
	ds_bpermute_b32 v30, v252, v28
	s_waitcnt lgkmcnt(0)
	v_add_f32_e32 v28, v28, v30
	ds_bpermute_b32 v30, v246, v28
	s_waitcnt lgkmcnt(0)
	v_add_f32_e32 v28, v28, v30
	v_fmamk_f32 v28, v28, 0x3a800000, v247
	v_mul_f32_e32 v30, 0x4b800000, v28
	v_cmp_gt_f32_e32 vcc, s35, v28
	s_nop 1
	v_cndmask_b32_e32 v28, v28, v30, vcc
	v_rsq_f32_e32 v28, v28
	s_nop 0
	v_mul_f32_e32 v30, 0x45800000, v28
	v_cndmask_b32_e32 v42, v28, v30, vcc
	v_pk_mul_f32 v[16:17], v[42:43], v[16:17] op_sel_hi:[0,1]
	v_pk_mul_f32 v[18:19], v[42:43], v[18:19] op_sel_hi:[0,1]
	v_pk_fma_f32 v[18:19], v[88:89], v[18:19], v[46:47]
	v_pk_fma_f32 v[16:17], v[86:87], v[16:17], v[44:45]
	s_and_b64 vcc, exec, s[6:7]
	v_lshl_add_u64 v[44:45], v[134:135], 2, s[0:1]
	s_cbranch_vccnz .LBB0_847
	global_store_dwordx4 v[44:45], v[16:19], off
	s_cbranch_execnz .LBB0_626

.LBB0_637:
	s_waitcnt vmcnt(56)
	v_and_b32_e32 v17, 0xffff0000, v132
	v_and_b32_e32 v19, 0xffff0000, v133
	v_lshlrev_b32_e32 v16, 16, v132
	v_lshlrev_b32_e32 v18, 16, v133
	v_mul_f32_e32 v20, v19, v19
	v_and_b32_e32 v23, 0xffff0000, v131
	v_and_b32_e32 v22, 0xffff0000, v130
	v_and_b32_e32 v29, 0xffff0000, v126
	v_mul_f32_e32 v28, v17, v17
	v_pk_fma_f32 v[42:43], v[18:19], v[18:19], v[20:21] op_sel_hi:[1,1,0]
	v_lshlrev_b32_e32 v21, 16, v131
	v_lshlrev_b32_e32 v20, 16, v130
	v_pk_mul_f32 v[24:25], v[22:23], v[22:23]
	v_lshlrev_b32_e32 v31, 16, v126
	v_pk_fma_f32 v[46:47], v[16:17], v[16:17], v[28:29] op_sel_hi:[1,1,0]
	v_pk_fma_f32 v[44:45], v[20:21], v[20:21], v[24:25]
	v_mov_b32_e32 v30, v46
	v_mov_b32_e32 v48, v42
	v_mov_b32_e32 v49, v31
	v_and_b32_e32 v25, 0xffff0000, v128
	v_mul_f32_e32 v126, v29, v29
	v_pk_add_f32 v[42:43], v[46:47], v[42:43]
	v_pk_mul_f32 v[46:47], v[30:31], v[48:49]
	v_pk_add_f32 v[44:45], v[44:45], v[44:45] op_sel:[0,1] op_sel_hi:[1,0]
	v_lshlrev_b32_e32 v24, 16, v128
	v_and_b32_e32 v27, 0xffff0000, v129
	v_mov_b32_e32 v43, v47
	v_mov_b32_e32 v45, v126
	v_mul_f32_e32 v28, v25, v25
	v_lshlrev_b32_e32 v26, 16, v129
	v_lshlrev_b32_e32 v40, 16, v127
	v_and_b32_e32 v41, 0xffff0000, v127
	v_pk_add_f32 v[42:43], v[42:43], v[44:45]
	v_pk_fma_f32 v[44:45], v[24:25], v[24:25], v[28:29] op_sel_hi:[1,1,0]
	v_mul_f32_e32 v28, v27, v27
	v_mul_f32_e32 v127, v40, v40
	v_mul_f32_e32 v128, v41, v41
	v_pk_fma_f32 v[46:47], v[26:27], v[26:27], v[28:29] op_sel_hi:[1,1,0]
	v_mov_b32_e32 v45, v127
	v_mov_b32_e32 v47, v128
	v_pk_add_f32 v[44:45], v[44:45], v[46:47]
	v_lshlrev_b32_e32 v46, 16, v125
	v_pk_add_f32 v[42:43], v[42:43], v[44:45]
	v_lshlrev_b32_e32 v44, 16, v124
	v_add_f32_e32 v28, v42, v43
	ds_bpermute_b32 v30, v144, v28
	v_and_b32_e32 v45, 0xffff0000, v124
	v_and_b32_e32 v47, 0xffff0000, v125
	s_waitcnt lgkmcnt(0)
	v_add_f32_e32 v28, v28, v30
	ds_bpermute_b32 v30, v228, v28
	s_waitcnt lgkmcnt(0)
	v_add_f32_e32 v28, v28, v30
	ds_bpermute_b32 v30, v250, v28
	s_waitcnt lgkmcnt(0)
	v_add_f32_e32 v28, v28, v30
	ds_bpermute_b32 v30, v251, v28
	s_waitcnt lgkmcnt(0)
	v_add_f32_e32 v28, v28, v30
	ds_bpermute_b32 v30, v252, v28
	s_waitcnt lgkmcnt(0)
	v_add_f32_e32 v28, v28, v30
	ds_bpermute_b32 v30, v246, v28
	s_waitcnt lgkmcnt(0)
	v_add_f32_e32 v28, v28, v30
	v_fmamk_f32 v28, v28, 0x3a800000, v247
	v_mul_f32_e32 v30, 0x4b800000, v28
	v_cmp_gt_f32_e32 vcc, s35, v28
	s_nop 1
	v_cndmask_b32_e32 v28, v28, v30, vcc
	v_rsq_f32_e32 v28, v28
	s_nop 0
	v_mul_f32_e32 v30, 0x45800000, v28
	v_cndmask_b32_e32 v42, v28, v30, vcc
	v_pk_mul_f32 v[16:17], v[42:43], v[16:17] op_sel_hi:[0,1]
	v_pk_mul_f32 v[18:19], v[42:43], v[18:19] op_sel_hi:[0,1]
	v_pk_fma_f32 v[18:19], v[88:89], v[18:19], v[46:47]
	v_pk_fma_f32 v[16:17], v[86:87], v[16:17], v[44:45]
	s_and_b64 vcc, exec, s[6:7]
	v_lshl_add_u64 v[44:45], v[114:115], 2, s[0:1]
	s_cbranch_vccnz .LBB0_851
	global_store_dwordx4 v[44:45], v[16:19], off
	s_cbranch_execnz .LBB0_640

.LBB0_651:
	s_waitcnt vmcnt(56)
	v_and_b32_e32 v17, 0xffff0000, v112
	v_and_b32_e32 v19, 0xffff0000, v113
	v_lshlrev_b32_e32 v16, 16, v112
	v_lshlrev_b32_e32 v18, 16, v113
	v_mul_f32_e32 v20, v19, v19
	v_and_b32_e32 v23, 0xffff0000, v111
	v_and_b32_e32 v22, 0xffff0000, v110
	v_and_b32_e32 v29, 0xffff0000, v106
	v_mul_f32_e32 v28, v17, v17
	v_pk_fma_f32 v[42:43], v[18:19], v[18:19], v[20:21] op_sel_hi:[1,1,0]
	v_lshlrev_b32_e32 v21, 16, v111
	v_lshlrev_b32_e32 v20, 16, v110
	v_pk_mul_f32 v[24:25], v[22:23], v[22:23]
	v_lshlrev_b32_e32 v31, 16, v106
	v_pk_fma_f32 v[46:47], v[16:17], v[16:17], v[28:29] op_sel_hi:[1,1,0]
	v_pk_fma_f32 v[44:45], v[20:21], v[20:21], v[24:25]
	v_mov_b32_e32 v30, v46
	v_mov_b32_e32 v48, v42
	v_mov_b32_e32 v49, v31
	v_and_b32_e32 v25, 0xffff0000, v108
	v_mul_f32_e32 v106, v29, v29
	v_pk_add_f32 v[42:43], v[46:47], v[42:43]
	v_pk_mul_f32 v[46:47], v[30:31], v[48:49]
	v_pk_add_f32 v[44:45], v[44:45], v[44:45] op_sel:[0,1] op_sel_hi:[1,0]
	v_lshlrev_b32_e32 v24, 16, v108
	v_and_b32_e32 v27, 0xffff0000, v109
	v_mov_b32_e32 v43, v47
	v_mov_b32_e32 v45, v106
	v_mul_f32_e32 v28, v25, v25
	v_lshlrev_b32_e32 v26, 16, v109
	v_lshlrev_b32_e32 v40, 16, v107
	v_and_b32_e32 v41, 0xffff0000, v107
	v_pk_add_f32 v[42:43], v[42:43], v[44:45]
	v_pk_fma_f32 v[44:45], v[24:25], v[24:25], v[28:29] op_sel_hi:[1,1,0]
	v_mul_f32_e32 v28, v27, v27
	v_mul_f32_e32 v107, v40, v40
	v_mul_f32_e32 v108, v41, v41
	v_pk_fma_f32 v[46:47], v[26:27], v[26:27], v[28:29] op_sel_hi:[1,1,0]
	v_mov_b32_e32 v45, v107
	v_mov_b32_e32 v47, v108
	v_pk_add_f32 v[44:45], v[44:45], v[46:47]
	v_lshlrev_b32_e32 v46, 16, v105
	v_pk_add_f32 v[42:43], v[42:43], v[44:45]
	v_lshlrev_b32_e32 v44, 16, v104
	v_add_f32_e32 v28, v42, v43
	ds_bpermute_b32 v30, v144, v28
	v_and_b32_e32 v45, 0xffff0000, v104
	v_and_b32_e32 v47, 0xffff0000, v105
	s_waitcnt lgkmcnt(0)
	v_add_f32_e32 v28, v28, v30
	ds_bpermute_b32 v30, v228, v28
	s_waitcnt lgkmcnt(0)
	v_add_f32_e32 v28, v28, v30
	ds_bpermute_b32 v30, v250, v28
	s_waitcnt lgkmcnt(0)
	v_add_f32_e32 v28, v28, v30
	ds_bpermute_b32 v30, v251, v28
	s_waitcnt lgkmcnt(0)
	v_add_f32_e32 v28, v28, v30
	ds_bpermute_b32 v30, v252, v28
	s_waitcnt lgkmcnt(0)
	v_add_f32_e32 v28, v28, v30
	ds_bpermute_b32 v30, v246, v28
	s_waitcnt lgkmcnt(0)
	v_add_f32_e32 v28, v28, v30
	v_fmamk_f32 v28, v28, 0x3a800000, v247
	v_mul_f32_e32 v30, 0x4b800000, v28
	v_cmp_gt_f32_e32 vcc, s35, v28
	s_nop 1
	v_cndmask_b32_e32 v28, v28, v30, vcc
	v_rsq_f32_e32 v28, v28
	s_nop 0
	v_mul_f32_e32 v30, 0x45800000, v28
	v_cndmask_b32_e32 v42, v28, v30, vcc
	v_pk_mul_f32 v[16:17], v[42:43], v[16:17] op_sel_hi:[0,1]
	v_pk_mul_f32 v[18:19], v[42:43], v[18:19] op_sel_hi:[0,1]
	v_pk_fma_f32 v[18:19], v[88:89], v[18:19], v[46:47]
	v_pk_fma_f32 v[16:17], v[86:87], v[16:17], v[44:45]
	s_and_b64 vcc, exec, s[6:7]
	v_lshl_add_u64 v[44:45], v[94:95], 2, s[0:1]
	s_cbranch_vccnz .LBB0_855
	global_store_dwordx4 v[44:45], v[16:19], off
	s_cbranch_execnz .LBB0_654

.LBB0_665:
	s_waitcnt vmcnt(56)
	v_and_b32_e32 v17, 0xffff0000, v84
	v_and_b32_e32 v19, 0xffff0000, v85
	v_lshlrev_b32_e32 v16, 16, v84
	v_lshlrev_b32_e32 v18, 16, v85
	v_mul_f32_e32 v20, v19, v19
	v_and_b32_e32 v23, 0xffff0000, v83
	v_and_b32_e32 v22, 0xffff0000, v82
	v_and_b32_e32 v29, 0xffff0000, v78
	v_mul_f32_e32 v28, v17, v17
	v_pk_fma_f32 v[42:43], v[18:19], v[18:19], v[20:21] op_sel_hi:[1,1,0]
	v_lshlrev_b32_e32 v21, 16, v83
	v_lshlrev_b32_e32 v20, 16, v82
	v_pk_mul_f32 v[24:25], v[22:23], v[22:23]
	v_lshlrev_b32_e32 v31, 16, v78
	v_pk_fma_f32 v[46:47], v[16:17], v[16:17], v[28:29] op_sel_hi:[1,1,0]
	v_pk_fma_f32 v[44:45], v[20:21], v[20:21], v[24:25]
	v_mov_b32_e32 v30, v46
	v_mov_b32_e32 v48, v42
	v_mov_b32_e32 v49, v31
	v_and_b32_e32 v25, 0xffff0000, v80
	v_mul_f32_e32 v78, v29, v29
	v_pk_add_f32 v[42:43], v[46:47], v[42:43]
	v_pk_mul_f32 v[46:47], v[30:31], v[48:49]
	v_pk_add_f32 v[44:45], v[44:45], v[44:45] op_sel:[0,1] op_sel_hi:[1,0]
	v_lshlrev_b32_e32 v24, 16, v80
	v_and_b32_e32 v27, 0xffff0000, v81
	v_mov_b32_e32 v43, v47
	v_mov_b32_e32 v45, v78
	v_mul_f32_e32 v28, v25, v25
	v_lshlrev_b32_e32 v26, 16, v81
	v_lshlrev_b32_e32 v40, 16, v79
	v_and_b32_e32 v41, 0xffff0000, v79
	v_pk_add_f32 v[42:43], v[42:43], v[44:45]
	v_pk_fma_f32 v[44:45], v[24:25], v[24:25], v[28:29] op_sel_hi:[1,1,0]
	v_mul_f32_e32 v28, v27, v27
	v_mul_f32_e32 v79, v40, v40
	v_mul_f32_e32 v80, v41, v41
	v_pk_fma_f32 v[46:47], v[26:27], v[26:27], v[28:29] op_sel_hi:[1,1,0]
	v_mov_b32_e32 v45, v79
	v_mov_b32_e32 v47, v80
	v_pk_add_f32 v[44:45], v[44:45], v[46:47]
	v_lshlrev_b32_e32 v46, 16, v77
	v_pk_add_f32 v[42:43], v[42:43], v[44:45]
	v_lshlrev_b32_e32 v44, 16, v76
	v_add_f32_e32 v28, v42, v43
	ds_bpermute_b32 v30, v144, v28
	v_and_b32_e32 v45, 0xffff0000, v76
	v_and_b32_e32 v47, 0xffff0000, v77
	s_waitcnt lgkmcnt(0)
	v_add_f32_e32 v28, v28, v30
	ds_bpermute_b32 v30, v228, v28
	s_waitcnt lgkmcnt(0)
	v_add_f32_e32 v28, v28, v30
	ds_bpermute_b32 v30, v250, v28
	s_waitcnt lgkmcnt(0)
	v_add_f32_e32 v28, v28, v30
	ds_bpermute_b32 v30, v251, v28
	s_waitcnt lgkmcnt(0)
	v_add_f32_e32 v28, v28, v30
	ds_bpermute_b32 v30, v252, v28
	s_waitcnt lgkmcnt(0)
	v_add_f32_e32 v28, v28, v30
	ds_bpermute_b32 v30, v246, v28
	s_waitcnt lgkmcnt(0)
	v_add_f32_e32 v28, v28, v30
	v_fmamk_f32 v28, v28, 0x3a800000, v247
	v_mul_f32_e32 v30, 0x4b800000, v28
	v_cmp_gt_f32_e32 vcc, s35, v28
	s_nop 1
	v_cndmask_b32_e32 v28, v28, v30, vcc
	v_rsq_f32_e32 v28, v28
	s_nop 0
	v_mul_f32_e32 v30, 0x45800000, v28
	v_cndmask_b32_e32 v42, v28, v30, vcc
	v_pk_mul_f32 v[16:17], v[42:43], v[16:17] op_sel_hi:[0,1]
	v_pk_mul_f32 v[18:19], v[42:43], v[18:19] op_sel_hi:[0,1]
	v_pk_fma_f32 v[18:19], v[88:89], v[18:19], v[46:47]
	v_pk_fma_f32 v[16:17], v[86:87], v[16:17], v[44:45]
	s_and_b64 vcc, exec, s[6:7]
	v_lshl_add_u64 v[44:45], v[66:67], 2, s[0:1]
	s_cbranch_vccnz .LBB0_859
	global_store_dwordx4 v[44:45], v[16:19], off
	s_cbranch_execnz .LBB0_668
